# score loop software-pipelined: MFMAs of the next key tile issue before the VALU epilogue of the current one (two accumulators), two K tiles in flight
# speedup vs baseline: 1.1494x; 1.0032x over previous
; DI void lds_barrier() { asm volatile("s_waitcnt lgkmcnt(0)" ::: "memory"); __builtin_amdgcn_s_barrier(); asm volatile("" ::: "memory"); }
; DI void selectA_item(const Params& p, int item, int next_item, char* lds, bf16x8 (&qf)[4], float (&wq)[16]) {
;     ...
;   const f32x4 pcv = ((const f32x4*)p.in[I_P])[(size_t)item * 512 + tid];
;   if (tid < 4) { mm[tid * 2] = 0xFFFFFFFFu; mm[tid * 2 + 1] = 0u; }
;   lds_barrier();
;   const bf16* Kt = (const bf16*)(p.ws + WS_IKS) + (size_t)b * 256 * 2048 + lane * 8;
;   {
;     bf16x8 kf[4], kn[4];
; #pragma unroll
;     for (int t = 0; t < 4; ++t) { kf[t] = (bf16x8){0, 0, 0, 0, 0, 0, 0, 0}; kn[t] = kf[t]; }
;     if (wid < ntile) {
; #pragma unroll
;       for (int t = 0; t < 4; ++t) kf[t] = *(const bf16x8*)(Kt + (size_t)wid * 2048 + t * 512);
;     }
;     float lo0 = INFINITY, hi0 = -INFINITY, lo1 = INFINITY, hi1 = -INFINITY;
;     for (int kt = wid; kt < ntile; kt += 8) {
;       if (kt + 8 < ntile) {
; #pragma unroll
;         for (int t = 0; t < 4; ++t) kn[t] = *(const bf16x8*)(Kt + (size_t)(kt + 8) * 2048 + t * 512);
;       }
.LBB0_405:
	s_andn2_b64 vcc, exec, s[4:5]
	s_cbranch_vccnz .LBB0_402
	v_readlane_b32 s4, v254, 3
	v_mov_b32_e32 v72, v182
	v_readlane_b32 s5, v254, 4
	s_load_dwordx2 s[4:5], s[4:5], 0x8
	s_ashr_i32 s3, s2, 31
	s_lshl_b64 s[6:7], s[2:3], 9
	v_ashrrev_i32_e32 v73, 31, v72
	v_lshl_add_u64 v[76:77], s[6:7], 0, v[72:73]
	s_waitcnt lgkmcnt(0)
	v_lshl_add_u64 v[0:1], v[76:77], 4, s[4:5]
	global_load_dwordx4 v[16:19], v[0:1], off
	v_cmp_gt_i32_e32 vcc, 4, v72
	s_and_saveexec_b64 s[4:5], vcc
	v_lshl_add_u32 v0, v72, 3, 0
	v_add_u32_e32 v0, 0x24060, v0
	ds_write_b64 v0, v[114:115]
	s_or_b64 exec, exec, s[4:5]
	s_ashr_i32 s52, s2, 11
	s_lshl_b32 s2, s2, 2
	s_and_b32 s2, s2, 0x1ffc
	v_writelane_b32 v254, s2, 58
	s_add_i32 s2, s2, 35
	s_waitcnt lgkmcnt(0)
	s_barrier
	v_ashrrev_i32_e32 v68, 6, v72
	s_lshr_b32 s8, s2, 5
	v_and_b32_e32 v67, 63, v72
	v_bfe_u32 v71, v72, 5, 1
	s_ashr_i32 s53, s52, 31
	v_cmp_gt_i32_e32 vcc, s8, v68
	s_and_saveexec_b64 s[2:3], vcc
	s_cbranch_execz .LBB0_415
	s_lshl_b64 s[4:5], s[52:53], 20
	v_readlane_b32 s6, v254, 24
	s_add_u32 s6, s6, s4
	v_readlane_b32 s7, v254, 25
	s_addc_u32 s7, s7, s5
	v_lshlrev_b32_e32 v48, 4, v67
	v_ashrrev_i32_e32 v69, 31, v68
	v_lshl_add_u64 v[0:1], s[6:7], 0, v[48:49]
	v_lshlrev_b64 v[4:5], 12, v[68:69]
	v_lshl_add_u64 v[6:7], v[0:1], 0, v[4:5]
	global_load_dwordx4 v[116:119], v[6:7], off
	global_load_dwordx4 v[62:65], v[6:7], off offset:1024
	global_load_dwordx4 v[58:61], v[6:7], off offset:2048
	global_load_dwordx4 v[54:57], v[6:7], off offset:3072
	v_lshlrev_b32_e32 v6, 7, v68
	v_mov_b32_e32 v48, v49
	v_and_b32_e32 v69, 31, v72
	v_lshl_add_u32 v6, v71, 16, v6
	v_lshl_add_u64 v[4:5], s[4:5], 0, v[4:5]
	v_readlane_b32 s4, v254, 47
	v_mov_b32_e32 v50, v49
	v_mov_b32_e32 v51, v49
	v_mov_b64_e32 v[20:21], v[48:49]
	v_mov_b64_e32 v[24:25], v[48:49]
	v_mov_b64_e32 v[28:29], v[48:49]
	v_lshl_or_b32 v6, v69, 2, v6
	v_lshl_or_b32 v4, v67, 4, v4
	v_readlane_b32 s5, v254, 48
	v_mov_b64_e32 v[22:23], v[50:51]
	v_mov_b64_e32 v[26:27], v[50:51]
	v_mov_b64_e32 v[30:31], v[50:51]
	v_mov_b64_e32 v[52:53], v[50:51]
	v_cmp_gt_u32_e32 vcc, 32, v67
	v_add_u32_e32 v79, 0, v6
	v_lshl_add_u64 v[80:81], s[4:5], 0, v[4:5]
	v_mov_b32_e32 v73, 0xff800000
	v_mov_b32_e32 v83, 0x7f800000
	s_mov_b64 s[4:5], 0
	v_mov_b64_e32 v[50:51], v[48:49]
	v_mov_b32_e32 v75, 0x7f800000
	v_mov_b32_e32 v48, 0xff800000
	v_mov_b32_e32 v84, v68
	v_readfirstlane_b32 s9, v68
	s_add_i32 s10, s9, 8
	s_cmp_lt_i32 s10, s8
	s_cbranch_scc0 .Lsc_p_noA
	global_load_dwordx4 v[20:23], v[80:81], off offset:-2048
	global_load_dwordx4 v[24:27], v[80:81], off offset:-1024
	global_load_dwordx4 v[28:31], v[80:81], off
	global_load_dwordx4 v[50:53], v[80:81], off offset:1024
	s_mov_b64 s[6:7], 0x8000
	v_lshl_add_u64 v[80:81], v[80:81], 0, s[6:7]
	s_add_i32 s10, s9, 16
	s_cmp_lt_i32 s10, s8
	s_cbranch_scc0 .Lsc_p_noB
	global_load_dwordx4 v[120:123], v[80:81], off offset:-2048
	global_load_dwordx4 v[124:127], v[80:81], off offset:-1024
	global_load_dwordx4 v[128:131], v[80:81], off
	global_load_dwordx4 v[132:135], v[80:81], off offset:1024
	s_mov_b64 s[6:7], 0x8000
	v_lshl_add_u64 v[80:81], v[80:81], 0, s[6:7]
	s_waitcnt vmcnt(8)
	s_branch .Lsc_pre2
.Lsc_p_noB:
	s_waitcnt vmcnt(4)
	s_branch .Lsc_pre2

; DI f32x16 mfma32(bf16x8 a, bf16x8 b, f32x16 c) { return __builtin_amdgcn_mfma_f32_32x32x16_bf16(a, b, c, 0, 0, 0); }
; DI void sel_load_qw(const Params& p, int item, bf16x8 (&qf)[4], float (&wq)[16], int lane) {
;     ...
;     wq[4 * q] = w4.x * 0.04419417382415922f; wq[4 * q + 1] = w4.y * 0.04419417382415922f; wq[4 * q + 2] = w4.z * 0.04419417382415922f; wq[4 * q + 3] = w4.w * 0.04419417382415922f; }
; DI void selectA_item(const Params& p, int item, int next_item, char* lds, bf16x8 (&qf)[4], float (&wq)[16]) {
;     ...
;     for (int kt = wid; kt < ntile; kt += 8) {
;       if (kt + 8 < ntile) {
; #pragma unroll
;         for (int t = 0; t < 4; ++t) kn[t] = *(const bf16x8*)(Kt + (size_t)(kt + 8) * 2048 + t * 512);
;       }
;       f32x16 s;
; #pragma unroll
;       for (int i = 0; i < 16; ++i) s[i] = 0.f;
; #pragma unroll
;       for (int t = 0; t < 4; ++t) s = mfma32(qf[t], kf[t], s);
.Lsc_pre2:
	v_mul_f32_e32 v98, 0x3d3504f3, v98
	v_mul_f32_e32 v99, 0x3d3504f3, v99
	v_mul_f32_e32 v100, 0x3d3504f3, v100
	v_mul_f32_e32 v101, 0x3d3504f3, v101
	v_mul_f32_e32 v102, 0x3d3504f3, v102
	v_mul_f32_e32 v103, 0x3d3504f3, v103
	v_mul_f32_e32 v104, 0x3d3504f3, v104
	v_mul_f32_e32 v105, 0x3d3504f3, v105
	v_mul_f32_e32 v106, 0x3d3504f3, v106
	v_mul_f32_e32 v107, 0x3d3504f3, v107
	v_mul_f32_e32 v108, 0x3d3504f3, v108
	v_mul_f32_e32 v109, 0x3d3504f3, v109
	v_mul_f32_e32 v110, 0x3d3504f3, v110
	v_mul_f32_e32 v111, 0x3d3504f3, v111
	v_mul_f32_e32 v112, 0x3d3504f3, v112
	v_mul_f32_e32 v113, 0x3d3504f3, v113
	v_mfma_f32_32x32x16_bf16 v[0:15], v[32:35], v[116:119], 0
	v_mfma_f32_32x32x16_bf16 v[0:15], v[36:39], v[62:65], v[0:15]
	v_mfma_f32_32x32x16_bf16 v[0:15], v[40:43], v[58:61], v[0:15]
	v_mfma_f32_32x32x16_bf16 v[0:15], v[44:47], v[54:57], v[0:15]
.Lsc_even:
	s_add_i32 s9, s9, 8
	s_cmp_lt_i32 s9, s8
	s_cbranch_scc0 .Lsc_last_even
	s_add_i32 s10, s9, 8
	s_cmp_lt_i32 s10, s8
	s_cbranch_scc0 .Lsc_even_w0
	s_waitcnt vmcnt(4)
	s_branch .Lsc_even_cp

; DI f32x16 mfma32(bf16x8 a, bf16x8 b, f32x16 c) { return __builtin_amdgcn_mfma_f32_32x32x16_bf16(a, b, c, 0, 0, 0); }
; DI float half_sum(float v) { auto rr = __builtin_amdgcn_permlane32_swap(__float_as_uint(v), __float_as_uint(v), false, false); return __uint_as_float(rr[0]) + __uint_as_float(rr[1]); }
; DI void selectA_item(const Params& p, int item, int next_item, char* lds, bf16x8 (&qf)[4], float (&wq)[16]) {
;     ...
;     for (int kt = wid; kt < ntile; kt += 8) {
;       if (kt + 8 < ntile) {
; #pragma unroll
;         for (int t = 0; t < 4; ++t) kn[t] = *(const bf16x8*)(Kt + (size_t)(kt + 8) * 2048 + t * 512);
;       }
;       f32x16 s;
; #pragma unroll
;       for (int i = 0; i < 16; ++i) s[i] = 0.f;
; #pragma unroll
;       for (int t = 0; t < 4; ++t) s = mfma32(qf[t], kf[t], s);
;       float v[4];
; #pragma unroll
;       for (int q = 0; q < 4; ++q) {
;         float a = wq[4 * q] * fmaxf(s[4 * q], 0.f);
; #pragma unroll
;         for (int jj = 1; jj < 4; ++jj) a += wq[4 * q + jj] * fmaxf(s[4 * q + jj], 0.f);
;         v[q] = half_sum(a) + 0.f;
;       }
;       const float va = h ? v[2] : v[0], vb = h ? v[3] : v[1];
;       const int key = kt * 32 + r32;
;       sc[(2 * h) * 8192 + key] = va; sc[(2 * h + 1) * 8192 + key] = vb;
;       lo0 = fminf(lo0, va); hi0 = fmaxf(hi0, va); lo1 = fminf(lo1, vb); hi1 = fmaxf(hi1, vb);
; #pragma unroll
;       for (int t = 0; t < 4; ++t) kf[t] = kn[t];
;     }
.Lsc_even_cp:
	v_mov_b64_e32 v[116:117], v[20:21]
	v_mov_b64_e32 v[118:119], v[22:23]
	v_mov_b64_e32 v[62:63], v[24:25]
	v_mov_b64_e32 v[64:65], v[26:27]
	v_mov_b64_e32 v[58:59], v[28:29]
	v_mov_b64_e32 v[60:61], v[30:31]
	v_mov_b64_e32 v[54:55], v[50:51]
	v_mov_b64_e32 v[56:57], v[52:53]
	s_add_i32 s10, s9, 16
	s_cmp_lt_i32 s10, s8
	s_cbranch_scc0 .Lsc_even_nl
	global_load_dwordx4 v[20:23], v[80:81], off offset:-2048
	global_load_dwordx4 v[24:27], v[80:81], off offset:-1024
	global_load_dwordx4 v[28:31], v[80:81], off
	global_load_dwordx4 v[50:53], v[80:81], off offset:1024
	s_mov_b64 s[6:7], 0x8000
	v_lshl_add_u64 v[80:81], v[80:81], 0, s[6:7]
.Lsc_even_nl:
	v_mfma_f32_32x32x16_bf16 v[136:151], v[32:35], v[116:119], 0
	v_mfma_f32_32x32x16_bf16 v[136:151], v[36:39], v[62:65], v[136:151]
	v_mfma_f32_32x32x16_bf16 v[136:151], v[40:43], v[58:61], v[136:151]
	v_mfma_f32_32x32x16_bf16 v[136:151], v[44:47], v[54:57], v[136:151]
	v_max_f32_e32 v0, 0, v0
	v_max_f32_e32 v1, 0, v1
	v_max_f32_e32 v2, 0, v2
	v_max_f32_e32 v3, 0, v3
	v_max_f32_e32 v4, 0, v4
	v_max_f32_e32 v5, 0, v5
	v_max_f32_e32 v6, 0, v6
	v_max_f32_e32 v7, 0, v7
	v_max_f32_e32 v8, 0, v8
	v_max_f32_e32 v9, 0, v9
	v_max_f32_e32 v10, 0, v10
	v_max_f32_e32 v11, 0, v11
	v_max_f32_e32 v12, 0, v12
	v_max_f32_e32 v13, 0, v13
	v_max_f32_e32 v14, 0, v14
	v_max_f32_e32 v15, 0, v15
	v_mul_f32_e32 v0, v106, v0
	v_mul_f32_e32 v4, v108, v4
	v_mul_f32_e32 v8, v110, v8
	v_mul_f32_e32 v12, v112, v12
	v_fmac_f32_e32 v0, v107, v1
	v_fmac_f32_e32 v4, v109, v5
	v_fmac_f32_e32 v8, v111, v9
	v_fmac_f32_e32 v12, v113, v13
	v_fmac_f32_e32 v0, v104, v2
	v_fmac_f32_e32 v4, v102, v6
	v_fmac_f32_e32 v8, v100, v10
	v_fmac_f32_e32 v12, v98, v14
	v_fmac_f32_e32 v0, v105, v3
	v_fmac_f32_e32 v4, v103, v7
	v_fmac_f32_e32 v8, v101, v11
	v_fmac_f32_e32 v12, v99, v15
	s_nop 1
	v_permlane32_swap_b32_e32 v0, v8
	v_permlane32_swap_b32_e32 v4, v12
	v_add_f32_e32 v0, v0, v8
	v_add_f32_e32 v4, v4, v12
	ds_write2st64_b32 v79, v0, v4 offset1:128
	v_min_f32_e32 v83, v83, v0
	v_max_f32_e32 v73, v73, v0
	v_min_f32_e32 v75, v75, v4
	v_max_f32_e32 v48, v48, v4
	v_add_u32_e32 v79, 0x400, v79

; DI f32x16 mfma32(bf16x8 a, bf16x8 b, f32x16 c) { return __builtin_amdgcn_mfma_f32_32x32x16_bf16(a, b, c, 0, 0, 0); }
; DI float half_sum(float v) { auto rr = __builtin_amdgcn_permlane32_swap(__float_as_uint(v), __float_as_uint(v), false, false); return __uint_as_float(rr[0]) + __uint_as_float(rr[1]); }
; DI void selectA_item(const Params& p, int item, int next_item, char* lds, bf16x8 (&qf)[4], float (&wq)[16]) {
;     ...
;     for (int kt = wid; kt < ntile; kt += 8) {
;       if (kt + 8 < ntile) {
; #pragma unroll
;         for (int t = 0; t < 4; ++t) kn[t] = *(const bf16x8*)(Kt + (size_t)(kt + 8) * 2048 + t * 512);
;       }
;       f32x16 s;
; #pragma unroll
;       for (int i = 0; i < 16; ++i) s[i] = 0.f;
; #pragma unroll
;       for (int t = 0; t < 4; ++t) s = mfma32(qf[t], kf[t], s);
;       float v[4];
; #pragma unroll
;       for (int q = 0; q < 4; ++q) {
;         float a = wq[4 * q] * fmaxf(s[4 * q], 0.f);
; #pragma unroll
;         for (int jj = 1; jj < 4; ++jj) a += wq[4 * q + jj] * fmaxf(s[4 * q + jj], 0.f);
;         v[q] = half_sum(a) + 0.f;
;       }
;       const float va = h ? v[2] : v[0], vb = h ? v[3] : v[1];
;       const int key = kt * 32 + r32;
;       sc[(2 * h) * 8192 + key] = va; sc[(2 * h + 1) * 8192 + key] = vb;
;       lo0 = fminf(lo0, va); hi0 = fmaxf(hi0, va); lo1 = fminf(lo1, vb); hi1 = fmaxf(hi1, vb);
; #pragma unroll
;       for (int t = 0; t < 4; ++t) kf[t] = kn[t];
;     }
.Lsc_odd_cp:
	v_mov_b64_e32 v[116:117], v[120:121]
	v_mov_b64_e32 v[118:119], v[122:123]
	v_mov_b64_e32 v[62:63], v[124:125]
	v_mov_b64_e32 v[64:65], v[126:127]
	v_mov_b64_e32 v[58:59], v[128:129]
	v_mov_b64_e32 v[60:61], v[130:131]
	v_mov_b64_e32 v[54:55], v[132:133]
	v_mov_b64_e32 v[56:57], v[134:135]
	s_add_i32 s10, s9, 16
	s_cmp_lt_i32 s10, s8
	s_cbranch_scc0 .Lsc_odd_nl
	global_load_dwordx4 v[120:123], v[80:81], off offset:-2048
	global_load_dwordx4 v[124:127], v[80:81], off offset:-1024
	global_load_dwordx4 v[128:131], v[80:81], off
	global_load_dwordx4 v[132:135], v[80:81], off offset:1024
	s_mov_b64 s[6:7], 0x8000
	v_lshl_add_u64 v[80:81], v[80:81], 0, s[6:7]
.Lsc_odd_nl:
	v_mfma_f32_32x32x16_bf16 v[0:15], v[32:35], v[116:119], 0
	v_mfma_f32_32x32x16_bf16 v[0:15], v[36:39], v[62:65], v[0:15]
	v_mfma_f32_32x32x16_bf16 v[0:15], v[40:43], v[58:61], v[0:15]
	v_mfma_f32_32x32x16_bf16 v[0:15], v[44:47], v[54:57], v[0:15]
	v_max_f32_e32 v136, 0, v136
	v_max_f32_e32 v137, 0, v137
	v_max_f32_e32 v138, 0, v138
	v_max_f32_e32 v139, 0, v139
	v_max_f32_e32 v140, 0, v140
	v_max_f32_e32 v141, 0, v141
	v_max_f32_e32 v142, 0, v142
	v_max_f32_e32 v143, 0, v143
	v_max_f32_e32 v144, 0, v144
	v_max_f32_e32 v145, 0, v145
	v_max_f32_e32 v146, 0, v146
	v_max_f32_e32 v147, 0, v147
	v_max_f32_e32 v148, 0, v148
	v_max_f32_e32 v149, 0, v149
	v_max_f32_e32 v150, 0, v150
	v_max_f32_e32 v151, 0, v151
	v_mul_f32_e32 v136, v106, v136
	v_mul_f32_e32 v140, v108, v140
	v_mul_f32_e32 v144, v110, v144
	v_mul_f32_e32 v148, v112, v148
	v_fmac_f32_e32 v136, v107, v137
	v_fmac_f32_e32 v140, v109, v141
	v_fmac_f32_e32 v144, v111, v145
	v_fmac_f32_e32 v148, v113, v149
	v_fmac_f32_e32 v136, v104, v138
	v_fmac_f32_e32 v140, v102, v142
	v_fmac_f32_e32 v144, v100, v146
	v_fmac_f32_e32 v148, v98, v150
	v_fmac_f32_e32 v136, v105, v139
	v_fmac_f32_e32 v140, v103, v143
	v_fmac_f32_e32 v144, v101, v147
	v_fmac_f32_e32 v148, v99, v151
	s_nop 1
	v_permlane32_swap_b32_e32 v136, v144
	v_permlane32_swap_b32_e32 v140, v148
	v_add_f32_e32 v136, v136, v144
	v_add_f32_e32 v140, v140, v148
	ds_write2st64_b32 v79, v136, v140 offset1:128
	v_min_f32_e32 v83, v83, v136
	v_max_f32_e32 v73, v73, v136
	v_min_f32_e32 v75, v75, v140
	v_max_f32_e32 v48, v48, v140
	v_add_u32_e32 v79, 0x400, v79
	s_branch .Lsc_even
.Lsc_last_even:
	s_nop 11
	v_max_f32_e32 v0, 0, v0
	v_max_f32_e32 v1, 0, v1
	v_max_f32_e32 v2, 0, v2
	v_max_f32_e32 v3, 0, v3
	v_max_f32_e32 v4, 0, v4
	v_max_f32_e32 v5, 0, v5
	v_max_f32_e32 v6, 0, v6
	v_max_f32_e32 v7, 0, v7
	v_max_f32_e32 v8, 0, v8
	v_max_f32_e32 v9, 0, v9
	v_max_f32_e32 v10, 0, v10
	v_max_f32_e32 v11, 0, v11
	v_max_f32_e32 v12, 0, v12
	v_max_f32_e32 v13, 0, v13
	v_max_f32_e32 v14, 0, v14
	v_max_f32_e32 v15, 0, v15
	v_mul_f32_e32 v0, v106, v0
	v_mul_f32_e32 v4, v108, v4
	v_mul_f32_e32 v8, v110, v8
	v_mul_f32_e32 v12, v112, v12
	v_fmac_f32_e32 v0, v107, v1
	v_fmac_f32_e32 v4, v109, v5
	v_fmac_f32_e32 v8, v111, v9
	v_fmac_f32_e32 v12, v113, v13
	v_fmac_f32_e32 v0, v104, v2
	v_fmac_f32_e32 v4, v102, v6
	v_fmac_f32_e32 v8, v100, v10
	v_fmac_f32_e32 v12, v98, v14
	v_fmac_f32_e32 v0, v105, v3
	v_fmac_f32_e32 v4, v103, v7
	v_fmac_f32_e32 v8, v101, v11
	v_fmac_f32_e32 v12, v99, v15
	s_nop 1
	v_permlane32_swap_b32_e32 v0, v8
	v_permlane32_swap_b32_e32 v4, v12
	v_add_f32_e32 v0, v0, v8
	v_add_f32_e32 v4, v4, v12
	ds_write2st64_b32 v79, v0, v4 offset1:128
	v_min_f32_e32 v83, v83, v0
	v_max_f32_e32 v73, v73, v0
	v_min_f32_e32 v75, v75, v4
	v_max_f32_e32 v48, v48, v4
	v_add_u32_e32 v79, 0x400, v79
	s_branch .Lsc_exit
.Lsc_last_odd:
	s_nop 11
	v_max_f32_e32 v136, 0, v136
	v_max_f32_e32 v137, 0, v137
	v_max_f32_e32 v138, 0, v138
	v_max_f32_e32 v139, 0, v139
	v_max_f32_e32 v140, 0, v140
	v_max_f32_e32 v141, 0, v141
	v_max_f32_e32 v142, 0, v142
	v_max_f32_e32 v143, 0, v143
	v_max_f32_e32 v144, 0, v144
	v_max_f32_e32 v145, 0, v145
	v_max_f32_e32 v146, 0, v146
	v_max_f32_e32 v147, 0, v147
	v_max_f32_e32 v148, 0, v148
	v_max_f32_e32 v149, 0, v149
	v_max_f32_e32 v150, 0, v150
	v_max_f32_e32 v151, 0, v151
	v_mul_f32_e32 v136, v106, v136
	v_mul_f32_e32 v140, v108, v140
	v_mul_f32_e32 v144, v110, v144
	v_mul_f32_e32 v148, v112, v148
	v_fmac_f32_e32 v136, v107, v137
	v_fmac_f32_e32 v140, v109, v141
	v_fmac_f32_e32 v144, v111, v145
	v_fmac_f32_e32 v148, v113, v149
	v_fmac_f32_e32 v136, v104, v138
	v_fmac_f32_e32 v140, v102, v142
	v_fmac_f32_e32 v144, v100, v146
	v_fmac_f32_e32 v148, v98, v150
	v_fmac_f32_e32 v136, v105, v139
	v_fmac_f32_e32 v140, v103, v143
	v_fmac_f32_e32 v144, v101, v147
	v_fmac_f32_e32 v148, v99, v151
	s_nop 1
	v_permlane32_swap_b32_e32 v136, v144
	v_permlane32_swap_b32_e32 v140, v148
	v_add_f32_e32 v136, v136, v144
	v_add_f32_e32 v140, v140, v148
	ds_write2st64_b32 v79, v136, v140 offset1:128
	v_min_f32_e32 v83, v83, v136
	v_max_f32_e32 v73, v73, v136
	v_min_f32_e32 v75, v75, v140
	v_max_f32_e32 v48, v48, v140
	v_add_u32_e32 v79, 0x400, v79
